# GEMM k-loop: LDS fragment reads interleaved as the M0 wait state between each M0 write and its LDS-DMA (no s_nop), DMA group first
# baseline (speedup 1.0000x reference)
; #define PG8_STAGE(bufoff, gbase, voff) do { _Pragma("unroll") for (int _i = 0; _i < 2; ++_i) \
;         __builtin_amdgcn_global_load_lds((const unsigned*)((const char*)(gbase) + (voff)[_i]), (LAS unsigned*)(lds + (bufoff) + ldsw + _i * 8192), 16, 0, 0); } while (0)
; #define PG8_LDA(dst, b, h) do { _Pragma("unroll") for (int m = 0; m < 4; ++m) _Pragma("unroll") for (int k = 0; k < 2; ++k) dst[m][k] = *(const LAS bf16x8*)(lds + PG8_SA(b, h) + aoff + m * 2048 + k * 1024); } while (0)
; #define PG8_LDB(dst, b, h) do { _Pragma("unroll") for (int n = 0; n < 2; ++n) _Pragma("unroll") for (int k = 0; k < 2; ++k) dst[n][k] = *(const LAS bf16x8*)(lds + PG8_SB(b, h) + boff + n * 2048 + k * 1024); } while (0)
; #define PG8_MMA(ai, bj, At, Bt) do { __builtin_amdgcn_s_setprio(1); _Pragma("unroll") for (int m = 0; m < 4; ++m) _Pragma("unroll") for (int n = 0; n < 2; ++n) _Pragma("unroll") for (int k = 0; k < 2; ++k) \
;         acc[ai][bj][m][n] = __builtin_amdgcn_mfma_f32_16x16x32_bf16(Bt[n][k], At[m][k], acc[ai][bj][m][n], 0, 0, 0); __builtin_amdgcn_s_setprio(0); } while (0)
; #define PG8_WAIT_V(n) asm volatile("s_waitcnt vmcnt(" #n ")" ::: "memory")
; template <class Epi>
; __device__ __forceinline__ void gemm_phase(LAS unsigned char* lds, const Gemm g, const StaticOrder& S, const Epi& E) {
;     ...
;         const bool has_next = S.next(ui + 1, nxt);
;         const char* nA = has_next ? (const char*)g.A + (size_t)nxt.pm * tstep : cA; const char* nB = has_next ? (const char*)g.Bt + (size_t)nxt.pn * tstep : cB;
;         for (int t = 0; t < nt; t += 2) {
;             const bool last = (t == nt - 2);
;             const char* a1 = cA + (size_t)(t + 1) * kstep;
;             const char* a2 = last ? nA : cA + (size_t)(t + 2) * kstep; const char* b2 = last ? nB : cB + (size_t)(t + 2) * kstep;
;             const char* a3 = a2 + kstep; const char* b3 = b2 + kstep;
;             PG8_LDB(B0, 0, 0); PG8_LDB(B1, 0, 1); PG8_SCHED; PG8_LDA(At, 0, 0); PG8_STAGE(PG8_SA(1, 1), a1 + hstep, voffA);
;             PG8_WAIT_V(8); PG8_WAIT_L(0); PG8_BAR; PG8_MMA(0, 0, At, B0); PG8_MMA(0, 1, At, B1); PG8_BAR; PG8_SCHED;
;             PG8_LDA(At, 0, 1); PG8_STAGE(PG8_SB(0, 0), b2, voffB); PG8_STAGE(PG8_SB(0, 1), b2 + hstep, voffB); PG8_STAGE(PG8_SA(0, 0), a2, voffA);
;             PG8_WAIT_V(8); PG8_WAIT_L(0); PG8_BAR; PG8_MMA(1, 0, At, B0); PG8_MMA(1, 1, At, B1); PG8_BAR; PG8_SCHED;
.LBB0_221:
	v_add_u32_e32 v216, 0x10000, v245
	v_add_u32_e32 v217, 0x14000, v245
	v_add_u32_e32 v218, 0x18000, v245
	v_add_u32_e32 v219, 0x1c000, v245
	s_add_u32 s0, s6, 0x80
	s_addc_u32 s1, s7, 0
	s_add_u32 s6, s4, 0x100
	s_addc_u32 s7, s5, 0
	s_mov_b32 s4, 0
	s_waitcnt vmcnt(0)
	s_add_i32 s71, s4, 2
	s_add_u32 s72, s0, 0x80
	s_addc_u32 s5, s1, 0
	s_cmp_eq_u32 s62, s4
	s_cselect_b32 s5, s49, s5
	s_cselect_b32 s4, s48, s72
	s_cselect_b32 s73, s51, s7
	s_cselect_b32 s72, s50, s6
	s_add_u32 s74, s72, s2
	s_addc_u32 s75, s73, 0
	s_add_u32 vcc_lo, s4, s2
	s_addc_u32 vcc_hi, s5, 0
	s_add_i32 m0, s55, 0xc000
	ds_read_b128 v[128:131], v216
	global_load_lds_dwordx4 v208, s[0:1]
	s_add_i32 m0, s55, 0xe000
	ds_read_b128 v[132:135], v216 offset:1024
	global_load_lds_dwordx4 v210, s[0:1]
	ds_read_b128 v[136:139], v216 offset:2048
	ds_read_b128 v[140:143], v216 offset:3072
	ds_read_b128 v[144:147], v217
	ds_read_b128 v[148:151], v217 offset:1024
	ds_read_b128 v[152:155], v217 offset:2048
	ds_read_b128 v[156:159], v217 offset:3072
	ds_read_b128 v[160:163], v247
	ds_read_b128 v[164:167], v247 offset:1024
	ds_read_b128 v[168:171], v247 offset:2048
	ds_read_b128 v[172:175], v247 offset:3072
	ds_read_b128 v[176:179], v247 offset:4096
	ds_read_b128 v[180:183], v247 offset:5120
	ds_read_b128 v[184:187], v247 offset:6144
	ds_read_b128 v[188:191], v247 offset:7168
	s_waitcnt vmcnt(8)
	s_waitcnt lgkmcnt(0)
	s_barrier
	s_setprio 1
	s_waitcnt lgkmcnt(0)
	v_mfma_f32_16x16x32_bf16 v[124:127], v[128:131], v[160:163], 0
	v_mfma_f32_16x16x32_bf16 v[120:123], v[136:139], v[160:163], 0
	v_mfma_f32_16x16x32_bf16 v[108:111], v[128:131], v[168:171], 0
	v_mfma_f32_16x16x32_bf16 v[104:107], v[136:139], v[168:171], 0
	v_mfma_f32_16x16x32_bf16 v[92:95], v[128:131], v[176:179], 0
	v_mfma_f32_16x16x32_bf16 v[88:91], v[136:139], v[176:179], 0
	v_mfma_f32_16x16x32_bf16 v[76:79], v[128:131], v[184:187], 0
	v_mfma_f32_16x16x32_bf16 v[72:75], v[136:139], v[184:187], 0
	v_mfma_f32_16x16x32_bf16 v[124:127], v[132:135], v[164:167], v[124:127]
	v_mfma_f32_16x16x32_bf16 v[120:123], v[140:143], v[164:167], v[120:123]
	v_mfma_f32_16x16x32_bf16 v[108:111], v[132:135], v[172:175], v[108:111]
	v_mfma_f32_16x16x32_bf16 v[104:107], v[140:143], v[172:175], v[104:107]
	v_mfma_f32_16x16x32_bf16 v[92:95], v[132:135], v[180:183], v[92:95]
	v_mfma_f32_16x16x32_bf16 v[88:91], v[140:143], v[180:183], v[88:91]
	v_mfma_f32_16x16x32_bf16 v[76:79], v[132:135], v[188:191], v[76:79]
	v_mfma_f32_16x16x32_bf16 v[72:75], v[140:143], v[188:191], v[72:75]
	s_setprio 0
	s_setprio 1
	v_mfma_f32_16x16x32_bf16 v[116:119], v[144:147], v[160:163], 0
	v_mfma_f32_16x16x32_bf16 v[112:115], v[152:155], v[160:163], 0
	v_mfma_f32_16x16x32_bf16 v[100:103], v[144:147], v[168:171], 0
	v_mfma_f32_16x16x32_bf16 v[96:99], v[152:155], v[168:171], 0
	v_mfma_f32_16x16x32_bf16 v[84:87], v[144:147], v[176:179], 0
	v_mfma_f32_16x16x32_bf16 v[80:83], v[152:155], v[176:179], 0
	v_mfma_f32_16x16x32_bf16 v[68:71], v[144:147], v[184:187], 0
	v_mfma_f32_16x16x32_bf16 v[64:67], v[152:155], v[184:187], 0
	v_mfma_f32_16x16x32_bf16 v[116:119], v[148:151], v[164:167], v[116:119]
	v_mfma_f32_16x16x32_bf16 v[112:115], v[156:159], v[164:167], v[112:115]
	v_mfma_f32_16x16x32_bf16 v[100:103], v[148:151], v[172:175], v[100:103]
	v_mfma_f32_16x16x32_bf16 v[96:99], v[156:159], v[172:175], v[96:99]
	v_mfma_f32_16x16x32_bf16 v[84:87], v[148:151], v[180:183], v[84:87]
	v_mfma_f32_16x16x32_bf16 v[80:83], v[156:159], v[180:183], v[80:83]
	v_mfma_f32_16x16x32_bf16 v[68:71], v[148:151], v[188:191], v[68:71]
	v_mfma_f32_16x16x32_bf16 v[64:67], v[156:159], v[188:191], v[64:67]
	s_setprio 0
	s_barrier
	s_add_i32 m0, s54, 0x10000
	ds_read_b128 v[160:163], v247 offset:16384
	global_load_lds_dwordx4 v192, s[72:73]
	s_add_i32 m0, s54, 0x12000
	ds_read_b128 v[164:167], v247 offset:17408
	global_load_lds_dwordx4 v204, s[72:73]
	s_add_i32 m0, s54, 0x14000
	ds_read_b128 v[168:171], v247 offset:18432
	global_load_lds_dwordx4 v192, s[74:75]
	s_add_i32 m0, s54, 0x16000
	ds_read_b128 v[172:175], v247 offset:19456
	global_load_lds_dwordx4 v204, s[74:75]
	s_mov_b32 m0, s55
	ds_read_b128 v[176:179], v247 offset:20480
	global_load_lds_dwordx4 v200, s[4:5]
	s_mov_b32 m0, s56
	ds_read_b128 v[180:183], v247 offset:21504
	global_load_lds_dwordx4 v202, s[4:5]
	ds_read_b128 v[184:187], v247 offset:22528
	ds_read_b128 v[188:191], v247 offset:23552
	s_waitcnt vmcnt(8)
	s_waitcnt lgkmcnt(0)
	s_barrier
	s_setprio 1
	s_waitcnt lgkmcnt(0)
	v_mfma_f32_16x16x32_bf16 v[60:63], v[128:131], v[160:163], 0
	v_mfma_f32_16x16x32_bf16 v[56:59], v[136:139], v[160:163], 0
	v_mfma_f32_16x16x32_bf16 v[44:47], v[128:131], v[168:171], 0
	v_mfma_f32_16x16x32_bf16 v[40:43], v[136:139], v[168:171], 0
	v_mfma_f32_16x16x32_bf16 v[28:31], v[128:131], v[176:179], 0
	v_mfma_f32_16x16x32_bf16 v[24:27], v[136:139], v[176:179], 0
	v_mfma_f32_16x16x32_bf16 v[12:15], v[128:131], v[184:187], 0
	v_mfma_f32_16x16x32_bf16 v[8:11], v[136:139], v[184:187], 0
	v_mfma_f32_16x16x32_bf16 v[60:63], v[132:135], v[164:167], v[60:63]
	v_mfma_f32_16x16x32_bf16 v[56:59], v[140:143], v[164:167], v[56:59]
	v_mfma_f32_16x16x32_bf16 v[44:47], v[132:135], v[172:175], v[44:47]
	v_mfma_f32_16x16x32_bf16 v[40:43], v[140:143], v[172:175], v[40:43]
	v_mfma_f32_16x16x32_bf16 v[28:31], v[132:135], v[180:183], v[28:31]
	v_mfma_f32_16x16x32_bf16 v[24:27], v[140:143], v[180:183], v[24:27]
	v_mfma_f32_16x16x32_bf16 v[12:15], v[132:135], v[188:191], v[12:15]
	v_mfma_f32_16x16x32_bf16 v[8:11], v[140:143], v[188:191], v[8:11]
	s_setprio 0
	s_setprio 1
	v_mfma_f32_16x16x32_bf16 v[52:55], v[144:147], v[160:163], 0
	v_mfma_f32_16x16x32_bf16 v[48:51], v[152:155], v[160:163], 0
	v_mfma_f32_16x16x32_bf16 v[36:39], v[144:147], v[168:171], 0
	v_mfma_f32_16x16x32_bf16 v[32:35], v[152:155], v[168:171], 0
	v_mfma_f32_16x16x32_bf16 v[20:23], v[144:147], v[176:179], 0
	v_mfma_f32_16x16x32_bf16 v[16:19], v[152:155], v[176:179], 0
	v_mfma_f32_16x16x32_bf16 v[4:7], v[144:147], v[184:187], 0
	v_mfma_f32_16x16x32_bf16 v[0:3], v[152:155], v[184:187], 0
	v_mfma_f32_16x16x32_bf16 v[52:55], v[148:151], v[164:167], v[52:55]
	v_mfma_f32_16x16x32_bf16 v[48:51], v[156:159], v[164:167], v[48:51]
	v_mfma_f32_16x16x32_bf16 v[36:39], v[148:151], v[172:175], v[36:39]
	v_mfma_f32_16x16x32_bf16 v[32:35], v[156:159], v[172:175], v[32:35]
	v_mfma_f32_16x16x32_bf16 v[20:23], v[148:151], v[180:183], v[20:23]
	v_mfma_f32_16x16x32_bf16 v[16:19], v[156:159], v[180:183], v[16:19]
	v_mfma_f32_16x16x32_bf16 v[4:7], v[148:151], v[188:191], v[4:7]
	v_mfma_f32_16x16x32_bf16 v[0:3], v[156:159], v[188:191], v[0:3]
	s_setprio 0
	s_barrier
; #define PG8_STAGE(bufoff, gbase, voff) do { _Pragma("unroll") for (int _i = 0; _i < 2; ++_i) \
;         __builtin_amdgcn_global_load_lds((const unsigned*)((const char*)(gbase) + (voff)[_i]), (LAS unsigned*)(lds + (bufoff) + ldsw + _i * 8192), 16, 0, 0); } while (0)
; #define PG8_LDA(dst, b, h) do { _Pragma("unroll") for (int m = 0; m < 4; ++m) _Pragma("unroll") for (int k = 0; k < 2; ++k) dst[m][k] = *(const LAS bf16x8*)(lds + PG8_SA(b, h) + aoff + m * 2048 + k * 1024); } while (0)
; #define PG8_LDB(dst, b, h) do { _Pragma("unroll") for (int n = 0; n < 2; ++n) _Pragma("unroll") for (int k = 0; k < 2; ++k) dst[n][k] = *(const LAS bf16x8*)(lds + PG8_SB(b, h) + boff + n * 2048 + k * 1024); } while (0)
; #define PG8_MMA(ai, bj, At, Bt) do { __builtin_amdgcn_s_setprio(1); _Pragma("unroll") for (int m = 0; m < 4; ++m) _Pragma("unroll") for (int n = 0; n < 2; ++n) _Pragma("unroll") for (int k = 0; k < 2; ++k) \
;         acc[ai][bj][m][n] = __builtin_amdgcn_mfma_f32_16x16x32_bf16(Bt[n][k], At[m][k], acc[ai][bj][m][n], 0, 0, 0); __builtin_amdgcn_s_setprio(0); } while (0)
; #define PG8_WAIT_V(n) asm volatile("s_waitcnt vmcnt(" #n ")" ::: "memory")
; #define PG8_WAIT_L(n) asm volatile("s_waitcnt lgkmcnt(" #n ")" ::: "memory")
; #define PG8_BAR __builtin_amdgcn_s_barrier()
; #define PG8_SCHED __builtin_amdgcn_sched_barrier(0)
; template <class Epi>
; __device__ __forceinline__ void gemm_phase(LAS unsigned char* lds, const Gemm g, const StaticOrder& S, const Epi& E) {
;     ...
;             PG8_LDB(B0, 1, 0); PG8_LDB(B1, 1, 1); PG8_SCHED; PG8_LDA(At, 1, 0); PG8_STAGE(PG8_SA(0, 1), a2 + hstep, voffA);
;             PG8_WAIT_V(8); PG8_WAIT_L(0); PG8_BAR; PG8_MMA(0, 0, At, B0); PG8_MMA(0, 1, At, B1); PG8_BAR; PG8_SCHED;
;             PG8_LDA(At, 1, 1); PG8_STAGE(PG8_SB(1, 0), b3, voffB); PG8_STAGE(PG8_SB(1, 1), b3 + hstep, voffB); PG8_STAGE(PG8_SA(1, 0), a3, voffA);
;             PG8_WAIT_V(8); PG8_WAIT_L(0); PG8_BAR; PG8_MMA(1, 0, At, B0); PG8_MMA(1, 1, At, B1); PG8_BAR; PG8_SCHED;
;         }
	s_mov_b32 m0, s57
	ds_read_b128 v[128:131], v218
	global_load_lds_dwordx4 v200, vcc
	s_mov_b32 m0, s58
	ds_read_b128 v[132:135], v218 offset:1024
	global_load_lds_dwordx4 v202, vcc
	ds_read_b128 v[136:139], v218 offset:2048
	ds_read_b128 v[140:143], v218 offset:3072
	ds_read_b128 v[144:147], v219
	ds_read_b128 v[148:151], v219 offset:1024
	ds_read_b128 v[152:155], v219 offset:2048
	ds_read_b128 v[156:159], v219 offset:3072
	ds_read_b128 v[160:163], v247 offset:32768
	ds_read_b128 v[164:167], v247 offset:33792
	ds_read_b128 v[168:171], v247 offset:34816
	ds_read_b128 v[172:175], v247 offset:35840
	ds_read_b128 v[176:179], v247 offset:36864
	ds_read_b128 v[180:183], v247 offset:37888
	ds_read_b128 v[184:187], v247 offset:38912
	ds_read_b128 v[188:191], v247 offset:39936
	s_waitcnt vmcnt(8)
	s_waitcnt lgkmcnt(0)
	s_barrier
	s_setprio 1
	s_waitcnt lgkmcnt(0)
	v_mfma_f32_16x16x32_bf16 v[124:127], v[128:131], v[160:163], v[124:127]
	v_mfma_f32_16x16x32_bf16 v[120:123], v[136:139], v[160:163], v[120:123]
	v_mfma_f32_16x16x32_bf16 v[108:111], v[128:131], v[168:171], v[108:111]
	v_mfma_f32_16x16x32_bf16 v[104:107], v[136:139], v[168:171], v[104:107]
	v_mfma_f32_16x16x32_bf16 v[92:95], v[128:131], v[176:179], v[92:95]
	v_mfma_f32_16x16x32_bf16 v[88:91], v[136:139], v[176:179], v[88:91]
	v_mfma_f32_16x16x32_bf16 v[76:79], v[128:131], v[184:187], v[76:79]
	v_mfma_f32_16x16x32_bf16 v[72:75], v[136:139], v[184:187], v[72:75]
	v_mfma_f32_16x16x32_bf16 v[124:127], v[132:135], v[164:167], v[124:127]
	v_mfma_f32_16x16x32_bf16 v[120:123], v[140:143], v[164:167], v[120:123]
	v_mfma_f32_16x16x32_bf16 v[108:111], v[132:135], v[172:175], v[108:111]
	v_mfma_f32_16x16x32_bf16 v[104:107], v[140:143], v[172:175], v[104:107]
	v_mfma_f32_16x16x32_bf16 v[92:95], v[132:135], v[180:183], v[92:95]
	v_mfma_f32_16x16x32_bf16 v[88:91], v[140:143], v[180:183], v[88:91]
	v_mfma_f32_16x16x32_bf16 v[76:79], v[132:135], v[188:191], v[76:79]
	v_mfma_f32_16x16x32_bf16 v[72:75], v[140:143], v[188:191], v[72:75]
	s_setprio 0
	s_setprio 1
	v_mfma_f32_16x16x32_bf16 v[116:119], v[144:147], v[160:163], v[116:119]
	v_mfma_f32_16x16x32_bf16 v[112:115], v[152:155], v[160:163], v[112:115]
	v_mfma_f32_16x16x32_bf16 v[100:103], v[144:147], v[168:171], v[100:103]
	v_mfma_f32_16x16x32_bf16 v[96:99], v[152:155], v[168:171], v[96:99]
	v_mfma_f32_16x16x32_bf16 v[84:87], v[144:147], v[176:179], v[84:87]
	v_mfma_f32_16x16x32_bf16 v[80:83], v[152:155], v[176:179], v[80:83]
	v_mfma_f32_16x16x32_bf16 v[68:71], v[144:147], v[184:187], v[68:71]
	v_mfma_f32_16x16x32_bf16 v[64:67], v[152:155], v[184:187], v[64:67]
	v_mfma_f32_16x16x32_bf16 v[116:119], v[148:151], v[164:167], v[116:119]
	v_mfma_f32_16x16x32_bf16 v[112:115], v[156:159], v[164:167], v[112:115]
	v_mfma_f32_16x16x32_bf16 v[100:103], v[148:151], v[172:175], v[100:103]
	v_mfma_f32_16x16x32_bf16 v[96:99], v[156:159], v[172:175], v[96:99]
	v_mfma_f32_16x16x32_bf16 v[84:87], v[148:151], v[180:183], v[84:87]
	v_mfma_f32_16x16x32_bf16 v[80:83], v[156:159], v[180:183], v[80:83]
	v_mfma_f32_16x16x32_bf16 v[68:71], v[148:151], v[188:191], v[68:71]
	v_mfma_f32_16x16x32_bf16 v[64:67], v[156:159], v[188:191], v[64:67]
	s_setprio 0
	s_barrier
	s_add_i32 m0, s54, 0x17f80
	ds_read_b128 v[160:163], v247 offset:49152
	global_load_lds_dwordx4 v192, s[72:73] offset:128
	s_add_i32 m0, s54, 0x19f80
	ds_read_b128 v[164:167], v247 offset:50176
	global_load_lds_dwordx4 v204, s[72:73] offset:128
	s_add_i32 m0, s54, 0x1bf80
	ds_read_b128 v[168:171], v247 offset:51200
	global_load_lds_dwordx4 v192, s[74:75] offset:128
	s_add_i32 m0, s54, 0x1df80
	ds_read_b128 v[172:175], v247 offset:52224
	global_load_lds_dwordx4 v204, s[74:75] offset:128
	s_add_i32 m0, s59, 0xffffff80
	ds_read_b128 v[176:179], v247 offset:53248
	global_load_lds_dwordx4 v200, s[4:5] offset:128
	s_add_i32 m0, s60, 0xffffff80
	ds_read_b128 v[180:183], v247 offset:54272
	global_load_lds_dwordx4 v202, s[4:5] offset:128
	ds_read_b128 v[184:187], v247 offset:55296
	ds_read_b128 v[188:191], v247 offset:56320
	s_waitcnt vmcnt(8)
	s_waitcnt lgkmcnt(0)
	s_barrier
	s_setprio 1
	s_waitcnt lgkmcnt(0)
	v_mfma_f32_16x16x32_bf16 v[60:63], v[128:131], v[160:163], v[60:63]
	v_mfma_f32_16x16x32_bf16 v[56:59], v[136:139], v[160:163], v[56:59]
	v_mfma_f32_16x16x32_bf16 v[44:47], v[128:131], v[168:171], v[44:47]
	v_mfma_f32_16x16x32_bf16 v[40:43], v[136:139], v[168:171], v[40:43]
	v_mfma_f32_16x16x32_bf16 v[28:31], v[128:131], v[176:179], v[28:31]
	v_mfma_f32_16x16x32_bf16 v[24:27], v[136:139], v[176:179], v[24:27]
	v_mfma_f32_16x16x32_bf16 v[12:15], v[128:131], v[184:187], v[12:15]
	v_mfma_f32_16x16x32_bf16 v[8:11], v[136:139], v[184:187], v[8:11]
	v_mfma_f32_16x16x32_bf16 v[60:63], v[132:135], v[164:167], v[60:63]
	v_mfma_f32_16x16x32_bf16 v[56:59], v[140:143], v[164:167], v[56:59]
	v_mfma_f32_16x16x32_bf16 v[44:47], v[132:135], v[172:175], v[44:47]
	v_mfma_f32_16x16x32_bf16 v[40:43], v[140:143], v[172:175], v[40:43]
	v_mfma_f32_16x16x32_bf16 v[28:31], v[132:135], v[180:183], v[28:31]
	v_mfma_f32_16x16x32_bf16 v[24:27], v[140:143], v[180:183], v[24:27]
	v_mfma_f32_16x16x32_bf16 v[12:15], v[132:135], v[188:191], v[12:15]
	v_mfma_f32_16x16x32_bf16 v[8:11], v[140:143], v[188:191], v[8:11]
	s_setprio 0
	s_setprio 1
	v_mfma_f32_16x16x32_bf16 v[52:55], v[144:147], v[160:163], v[52:55]
	v_mfma_f32_16x16x32_bf16 v[48:51], v[152:155], v[160:163], v[48:51]
	v_mfma_f32_16x16x32_bf16 v[36:39], v[144:147], v[168:171], v[36:39]
	v_mfma_f32_16x16x32_bf16 v[32:35], v[152:155], v[168:171], v[32:35]
	v_mfma_f32_16x16x32_bf16 v[20:23], v[144:147], v[176:179], v[20:23]
	v_mfma_f32_16x16x32_bf16 v[16:19], v[152:155], v[176:179], v[16:19]
	v_mfma_f32_16x16x32_bf16 v[4:7], v[144:147], v[184:187], v[4:7]
	v_mfma_f32_16x16x32_bf16 v[0:3], v[152:155], v[184:187], v[0:3]
	v_mfma_f32_16x16x32_bf16 v[52:55], v[148:151], v[164:167], v[52:55]
	v_mfma_f32_16x16x32_bf16 v[48:51], v[156:159], v[164:167], v[48:51]
	v_mfma_f32_16x16x32_bf16 v[36:39], v[148:151], v[172:175], v[36:39]
	v_mfma_f32_16x16x32_bf16 v[32:35], v[156:159], v[172:175], v[32:35]
	v_mfma_f32_16x16x32_bf16 v[20:23], v[148:151], v[180:183], v[20:23]
	v_mfma_f32_16x16x32_bf16 v[16:19], v[156:159], v[180:183], v[16:19]
	v_mfma_f32_16x16x32_bf16 v[4:7], v[148:151], v[188:191], v[4:7]
	v_mfma_f32_16x16x32_bf16 v[0:3], v[156:159], v[188:191], v[0:3]
	s_setprio 0
	s_barrier
	s_add_u32 s0, s0, 0x100
	s_addc_u32 s1, s1, 0
	s_add_u32 s6, s6, 0x100
	s_addc_u32 s7, s7, 0
	s_cmp_ge_u32 s71, s61
	s_mov_b32 s4, s71
	s_cbranch_scc1 .Lk_done
; #define PG8_STAGE(bufoff, gbase, voff) do { _Pragma("unroll") for (int _i = 0; _i < 2; ++_i) \
;         __builtin_amdgcn_global_load_lds((const unsigned*)((const char*)(gbase) + (voff)[_i]), (LAS unsigned*)(lds + (bufoff) + ldsw + _i * 8192), 16, 0, 0); } while (0)
; #define PG8_LDA(dst, b, h) do { _Pragma("unroll") for (int m = 0; m < 4; ++m) _Pragma("unroll") for (int k = 0; k < 2; ++k) dst[m][k] = *(const LAS bf16x8*)(lds + PG8_SA(b, h) + aoff + m * 2048 + k * 1024); } while (0)
; #define PG8_LDB(dst, b, h) do { _Pragma("unroll") for (int n = 0; n < 2; ++n) _Pragma("unroll") for (int k = 0; k < 2; ++k) dst[n][k] = *(const LAS bf16x8*)(lds + PG8_SB(b, h) + boff + n * 2048 + k * 1024); } while (0)
; #define PG8_MMA(ai, bj, At, Bt) do { __builtin_amdgcn_s_setprio(1); _Pragma("unroll") for (int m = 0; m < 4; ++m) _Pragma("unroll") for (int n = 0; n < 2; ++n) _Pragma("unroll") for (int k = 0; k < 2; ++k) \
;         acc[ai][bj][m][n] = __builtin_amdgcn_mfma_f32_16x16x32_bf16(Bt[n][k], At[m][k], acc[ai][bj][m][n], 0, 0, 0); __builtin_amdgcn_s_setprio(0); } while (0)
; #define PG8_WAIT_V(n) asm volatile("s_waitcnt vmcnt(" #n ")" ::: "memory")
; template <class Epi>
; __device__ __forceinline__ void gemm_phase(LAS unsigned char* lds, const Gemm g, const StaticOrder& S, const Epi& E) {
;     ...
;         const bool has_next = S.next(ui + 1, nxt);
;         const char* nA = has_next ? (const char*)g.A + (size_t)nxt.pm * tstep : cA; const char* nB = has_next ? (const char*)g.Bt + (size_t)nxt.pn * tstep : cB;
;         for (int t = 0; t < nt; t += 2) {
;             const bool last = (t == nt - 2);
;             const char* a1 = cA + (size_t)(t + 1) * kstep;
;             const char* a2 = last ? nA : cA + (size_t)(t + 2) * kstep; const char* b2 = last ? nB : cB + (size_t)(t + 2) * kstep;
;             const char* a3 = a2 + kstep; const char* b3 = b2 + kstep;
;             PG8_LDB(B0, 0, 0); PG8_LDB(B1, 0, 1); PG8_SCHED; PG8_LDA(At, 0, 0); PG8_STAGE(PG8_SA(1, 1), a1 + hstep, voffA);
;             PG8_WAIT_V(8); PG8_WAIT_L(0); PG8_BAR; PG8_MMA(0, 0, At, B0); PG8_MMA(0, 1, At, B1); PG8_BAR; PG8_SCHED;
;             PG8_LDA(At, 0, 1); PG8_STAGE(PG8_SB(0, 0), b2, voffB); PG8_STAGE(PG8_SB(0, 1), b2 + hstep, voffB); PG8_STAGE(PG8_SA(0, 0), a2, voffA);
;             PG8_WAIT_V(8); PG8_WAIT_L(0); PG8_BAR; PG8_MMA(1, 0, At, B0); PG8_MMA(1, 1, At, B1); PG8_BAR; PG8_SCHED;
.LBB0_222:
	s_add_i32 s71, s4, 2
	s_add_u32 s72, s0, 0x80
	s_addc_u32 s5, s1, 0
	s_cmp_eq_u32 s62, s4
	s_cselect_b32 s5, s49, s5
	s_cselect_b32 s4, s48, s72
	s_cselect_b32 s73, s51, s7
	s_cselect_b32 s72, s50, s6
	s_add_u32 s74, s72, s2
	s_addc_u32 s75, s73, 0
	s_add_u32 vcc_lo, s4, s2
	s_addc_u32 vcc_hi, s5, 0
	s_add_i32 m0, s55, 0xc000
	ds_read_b128 v[128:131], v216
	global_load_lds_dwordx4 v208, s[0:1]
	s_add_i32 m0, s55, 0xe000
	ds_read_b128 v[132:135], v216 offset:1024
	global_load_lds_dwordx4 v210, s[0:1]
	ds_read_b128 v[136:139], v216 offset:2048
	ds_read_b128 v[140:143], v216 offset:3072
	ds_read_b128 v[144:147], v217
	ds_read_b128 v[148:151], v217 offset:1024
	ds_read_b128 v[152:155], v217 offset:2048
	ds_read_b128 v[156:159], v217 offset:3072
	ds_read_b128 v[160:163], v247
	ds_read_b128 v[164:167], v247 offset:1024
	ds_read_b128 v[168:171], v247 offset:2048
	ds_read_b128 v[172:175], v247 offset:3072
	ds_read_b128 v[176:179], v247 offset:4096
	ds_read_b128 v[180:183], v247 offset:5120
	ds_read_b128 v[184:187], v247 offset:6144
	ds_read_b128 v[188:191], v247 offset:7168
	s_waitcnt vmcnt(8)
	s_waitcnt lgkmcnt(0)
	s_barrier
	s_setprio 1
	s_waitcnt lgkmcnt(0)
	v_mfma_f32_16x16x32_bf16 v[124:127], v[128:131], v[160:163], v[124:127]
	v_mfma_f32_16x16x32_bf16 v[120:123], v[136:139], v[160:163], v[120:123]
	v_mfma_f32_16x16x32_bf16 v[108:111], v[128:131], v[168:171], v[108:111]
	v_mfma_f32_16x16x32_bf16 v[104:107], v[136:139], v[168:171], v[104:107]
	v_mfma_f32_16x16x32_bf16 v[92:95], v[128:131], v[176:179], v[92:95]
	v_mfma_f32_16x16x32_bf16 v[88:91], v[136:139], v[176:179], v[88:91]
	v_mfma_f32_16x16x32_bf16 v[76:79], v[128:131], v[184:187], v[76:79]
	v_mfma_f32_16x16x32_bf16 v[72:75], v[136:139], v[184:187], v[72:75]
	v_mfma_f32_16x16x32_bf16 v[124:127], v[132:135], v[164:167], v[124:127]
	v_mfma_f32_16x16x32_bf16 v[120:123], v[140:143], v[164:167], v[120:123]
	v_mfma_f32_16x16x32_bf16 v[108:111], v[132:135], v[172:175], v[108:111]
	v_mfma_f32_16x16x32_bf16 v[104:107], v[140:143], v[172:175], v[104:107]
	v_mfma_f32_16x16x32_bf16 v[92:95], v[132:135], v[180:183], v[92:95]
	v_mfma_f32_16x16x32_bf16 v[88:91], v[140:143], v[180:183], v[88:91]
	v_mfma_f32_16x16x32_bf16 v[76:79], v[132:135], v[188:191], v[76:79]
	v_mfma_f32_16x16x32_bf16 v[72:75], v[140:143], v[188:191], v[72:75]
	s_setprio 0
	s_setprio 1
	v_mfma_f32_16x16x32_bf16 v[116:119], v[144:147], v[160:163], v[116:119]
	v_mfma_f32_16x16x32_bf16 v[112:115], v[152:155], v[160:163], v[112:115]
	v_mfma_f32_16x16x32_bf16 v[100:103], v[144:147], v[168:171], v[100:103]
	v_mfma_f32_16x16x32_bf16 v[96:99], v[152:155], v[168:171], v[96:99]
	v_mfma_f32_16x16x32_bf16 v[84:87], v[144:147], v[176:179], v[84:87]
	v_mfma_f32_16x16x32_bf16 v[80:83], v[152:155], v[176:179], v[80:83]
	v_mfma_f32_16x16x32_bf16 v[68:71], v[144:147], v[184:187], v[68:71]
	v_mfma_f32_16x16x32_bf16 v[64:67], v[152:155], v[184:187], v[64:67]
	v_mfma_f32_16x16x32_bf16 v[116:119], v[148:151], v[164:167], v[116:119]
	v_mfma_f32_16x16x32_bf16 v[112:115], v[156:159], v[164:167], v[112:115]
	v_mfma_f32_16x16x32_bf16 v[100:103], v[148:151], v[172:175], v[100:103]
	v_mfma_f32_16x16x32_bf16 v[96:99], v[156:159], v[172:175], v[96:99]
	v_mfma_f32_16x16x32_bf16 v[84:87], v[148:151], v[180:183], v[84:87]
	v_mfma_f32_16x16x32_bf16 v[80:83], v[156:159], v[180:183], v[80:83]
	v_mfma_f32_16x16x32_bf16 v[68:71], v[148:151], v[188:191], v[68:71]
	v_mfma_f32_16x16x32_bf16 v[64:67], v[156:159], v[188:191], v[64:67]
	s_setprio 0
	s_barrier
	s_add_i32 m0, s54, 0x10000
	ds_read_b128 v[160:163], v247 offset:16384
	global_load_lds_dwordx4 v192, s[72:73]
	s_add_i32 m0, s54, 0x12000
	ds_read_b128 v[164:167], v247 offset:17408
	global_load_lds_dwordx4 v204, s[72:73]
	s_add_i32 m0, s54, 0x14000
	ds_read_b128 v[168:171], v247 offset:18432
	global_load_lds_dwordx4 v192, s[74:75]
	s_add_i32 m0, s54, 0x16000
	ds_read_b128 v[172:175], v247 offset:19456
	global_load_lds_dwordx4 v204, s[74:75]
	s_mov_b32 m0, s55
	ds_read_b128 v[176:179], v247 offset:20480
	global_load_lds_dwordx4 v200, s[4:5]
	s_mov_b32 m0, s56
	ds_read_b128 v[180:183], v247 offset:21504
	global_load_lds_dwordx4 v202, s[4:5]
	ds_read_b128 v[184:187], v247 offset:22528
	ds_read_b128 v[188:191], v247 offset:23552
	s_waitcnt vmcnt(8)
	s_waitcnt lgkmcnt(0)
	s_barrier
	s_setprio 1
	s_waitcnt lgkmcnt(0)
	v_mfma_f32_16x16x32_bf16 v[60:63], v[128:131], v[160:163], v[60:63]
	v_mfma_f32_16x16x32_bf16 v[56:59], v[136:139], v[160:163], v[56:59]
	v_mfma_f32_16x16x32_bf16 v[44:47], v[128:131], v[168:171], v[44:47]
	v_mfma_f32_16x16x32_bf16 v[40:43], v[136:139], v[168:171], v[40:43]
	v_mfma_f32_16x16x32_bf16 v[28:31], v[128:131], v[176:179], v[28:31]
	v_mfma_f32_16x16x32_bf16 v[24:27], v[136:139], v[176:179], v[24:27]
	v_mfma_f32_16x16x32_bf16 v[12:15], v[128:131], v[184:187], v[12:15]
	v_mfma_f32_16x16x32_bf16 v[8:11], v[136:139], v[184:187], v[8:11]
	v_mfma_f32_16x16x32_bf16 v[60:63], v[132:135], v[164:167], v[60:63]
	v_mfma_f32_16x16x32_bf16 v[56:59], v[140:143], v[164:167], v[56:59]
	v_mfma_f32_16x16x32_bf16 v[44:47], v[132:135], v[172:175], v[44:47]
	v_mfma_f32_16x16x32_bf16 v[40:43], v[140:143], v[172:175], v[40:43]
	v_mfma_f32_16x16x32_bf16 v[28:31], v[132:135], v[180:183], v[28:31]
	v_mfma_f32_16x16x32_bf16 v[24:27], v[140:143], v[180:183], v[24:27]
	v_mfma_f32_16x16x32_bf16 v[12:15], v[132:135], v[188:191], v[12:15]
	v_mfma_f32_16x16x32_bf16 v[8:11], v[140:143], v[188:191], v[8:11]
	s_setprio 0
	s_setprio 1
	v_mfma_f32_16x16x32_bf16 v[52:55], v[144:147], v[160:163], v[52:55]
	v_mfma_f32_16x16x32_bf16 v[48:51], v[152:155], v[160:163], v[48:51]
	v_mfma_f32_16x16x32_bf16 v[36:39], v[144:147], v[168:171], v[36:39]
	v_mfma_f32_16x16x32_bf16 v[32:35], v[152:155], v[168:171], v[32:35]
	v_mfma_f32_16x16x32_bf16 v[20:23], v[144:147], v[176:179], v[20:23]
	v_mfma_f32_16x16x32_bf16 v[16:19], v[152:155], v[176:179], v[16:19]
	v_mfma_f32_16x16x32_bf16 v[4:7], v[144:147], v[184:187], v[4:7]
	v_mfma_f32_16x16x32_bf16 v[0:3], v[152:155], v[184:187], v[0:3]
	v_mfma_f32_16x16x32_bf16 v[52:55], v[148:151], v[164:167], v[52:55]
	v_mfma_f32_16x16x32_bf16 v[48:51], v[156:159], v[164:167], v[48:51]
	v_mfma_f32_16x16x32_bf16 v[36:39], v[148:151], v[172:175], v[36:39]
	v_mfma_f32_16x16x32_bf16 v[32:35], v[156:159], v[172:175], v[32:35]
	v_mfma_f32_16x16x32_bf16 v[20:23], v[148:151], v[180:183], v[20:23]
	v_mfma_f32_16x16x32_bf16 v[16:19], v[156:159], v[180:183], v[16:19]
	v_mfma_f32_16x16x32_bf16 v[4:7], v[148:151], v[188:191], v[4:7]
	v_mfma_f32_16x16x32_bf16 v[0:3], v[156:159], v[188:191], v[0:3]
	s_setprio 0
	s_barrier
; #define PG8_STAGE(bufoff, gbase, voff) do { _Pragma("unroll") for (int _i = 0; _i < 2; ++_i) \
;         __builtin_amdgcn_global_load_lds((const unsigned*)((const char*)(gbase) + (voff)[_i]), (LAS unsigned*)(lds + (bufoff) + ldsw + _i * 8192), 16, 0, 0); } while (0)
; #define PG8_LDA(dst, b, h) do { _Pragma("unroll") for (int m = 0; m < 4; ++m) _Pragma("unroll") for (int k = 0; k < 2; ++k) dst[m][k] = *(const LAS bf16x8*)(lds + PG8_SA(b, h) + aoff + m * 2048 + k * 1024); } while (0)
; #define PG8_LDB(dst, b, h) do { _Pragma("unroll") for (int n = 0; n < 2; ++n) _Pragma("unroll") for (int k = 0; k < 2; ++k) dst[n][k] = *(const LAS bf16x8*)(lds + PG8_SB(b, h) + boff + n * 2048 + k * 1024); } while (0)
; #define PG8_MMA(ai, bj, At, Bt) do { __builtin_amdgcn_s_setprio(1); _Pragma("unroll") for (int m = 0; m < 4; ++m) _Pragma("unroll") for (int n = 0; n < 2; ++n) _Pragma("unroll") for (int k = 0; k < 2; ++k) \
;         acc[ai][bj][m][n] = __builtin_amdgcn_mfma_f32_16x16x32_bf16(Bt[n][k], At[m][k], acc[ai][bj][m][n], 0, 0, 0); __builtin_amdgcn_s_setprio(0); } while (0)
; #define PG8_WAIT_V(n) asm volatile("s_waitcnt vmcnt(" #n ")" ::: "memory")
; #define PG8_WAIT_L(n) asm volatile("s_waitcnt lgkmcnt(" #n ")" ::: "memory")
; #define PG8_BAR __builtin_amdgcn_s_barrier()
; #define PG8_SCHED __builtin_amdgcn_sched_barrier(0)
; template <class Epi>
; __device__ __forceinline__ void gemm_phase(LAS unsigned char* lds, const Gemm g, const StaticOrder& S, const Epi& E) {
;     ...
;             PG8_LDB(B0, 1, 0); PG8_LDB(B1, 1, 1); PG8_SCHED; PG8_LDA(At, 1, 0); PG8_STAGE(PG8_SA(0, 1), a2 + hstep, voffA);
;             PG8_WAIT_V(8); PG8_WAIT_L(0); PG8_BAR; PG8_MMA(0, 0, At, B0); PG8_MMA(0, 1, At, B1); PG8_BAR; PG8_SCHED;
;             PG8_LDA(At, 1, 1); PG8_STAGE(PG8_SB(1, 0), b3, voffB); PG8_STAGE(PG8_SB(1, 1), b3 + hstep, voffB); PG8_STAGE(PG8_SA(1, 0), a3, voffA);
;             PG8_WAIT_V(8); PG8_WAIT_L(0); PG8_BAR; PG8_MMA(1, 0, At, B0); PG8_MMA(1, 1, At, B1); PG8_BAR; PG8_SCHED;
;         }
	s_mov_b32 m0, s57
	ds_read_b128 v[128:131], v218
	global_load_lds_dwordx4 v200, vcc
	s_mov_b32 m0, s58
	ds_read_b128 v[132:135], v218 offset:1024
	global_load_lds_dwordx4 v202, vcc
	ds_read_b128 v[136:139], v218 offset:2048
	ds_read_b128 v[140:143], v218 offset:3072
	ds_read_b128 v[144:147], v219
	ds_read_b128 v[148:151], v219 offset:1024
	ds_read_b128 v[152:155], v219 offset:2048
	ds_read_b128 v[156:159], v219 offset:3072
	ds_read_b128 v[160:163], v247 offset:32768
	ds_read_b128 v[164:167], v247 offset:33792
	ds_read_b128 v[168:171], v247 offset:34816
	ds_read_b128 v[172:175], v247 offset:35840
	ds_read_b128 v[176:179], v247 offset:36864
	ds_read_b128 v[180:183], v247 offset:37888
	ds_read_b128 v[184:187], v247 offset:38912
	ds_read_b128 v[188:191], v247 offset:39936
	s_waitcnt vmcnt(8)
	s_waitcnt lgkmcnt(0)
	s_barrier
	s_setprio 1
	s_waitcnt lgkmcnt(0)
	v_mfma_f32_16x16x32_bf16 v[124:127], v[128:131], v[160:163], v[124:127]
	v_mfma_f32_16x16x32_bf16 v[120:123], v[136:139], v[160:163], v[120:123]
	v_mfma_f32_16x16x32_bf16 v[108:111], v[128:131], v[168:171], v[108:111]
	v_mfma_f32_16x16x32_bf16 v[104:107], v[136:139], v[168:171], v[104:107]
	v_mfma_f32_16x16x32_bf16 v[92:95], v[128:131], v[176:179], v[92:95]
	v_mfma_f32_16x16x32_bf16 v[88:91], v[136:139], v[176:179], v[88:91]
	v_mfma_f32_16x16x32_bf16 v[76:79], v[128:131], v[184:187], v[76:79]
	v_mfma_f32_16x16x32_bf16 v[72:75], v[136:139], v[184:187], v[72:75]
	v_mfma_f32_16x16x32_bf16 v[124:127], v[132:135], v[164:167], v[124:127]
	v_mfma_f32_16x16x32_bf16 v[120:123], v[140:143], v[164:167], v[120:123]
	v_mfma_f32_16x16x32_bf16 v[108:111], v[132:135], v[172:175], v[108:111]
	v_mfma_f32_16x16x32_bf16 v[104:107], v[140:143], v[172:175], v[104:107]
	v_mfma_f32_16x16x32_bf16 v[92:95], v[132:135], v[180:183], v[92:95]
	v_mfma_f32_16x16x32_bf16 v[88:91], v[140:143], v[180:183], v[88:91]
	v_mfma_f32_16x16x32_bf16 v[76:79], v[132:135], v[188:191], v[76:79]
	v_mfma_f32_16x16x32_bf16 v[72:75], v[140:143], v[188:191], v[72:75]
	s_setprio 0
	s_setprio 1
	v_mfma_f32_16x16x32_bf16 v[116:119], v[144:147], v[160:163], v[116:119]
	v_mfma_f32_16x16x32_bf16 v[112:115], v[152:155], v[160:163], v[112:115]
	v_mfma_f32_16x16x32_bf16 v[100:103], v[144:147], v[168:171], v[100:103]
	v_mfma_f32_16x16x32_bf16 v[96:99], v[152:155], v[168:171], v[96:99]
	v_mfma_f32_16x16x32_bf16 v[84:87], v[144:147], v[176:179], v[84:87]
	v_mfma_f32_16x16x32_bf16 v[80:83], v[152:155], v[176:179], v[80:83]
	v_mfma_f32_16x16x32_bf16 v[68:71], v[144:147], v[184:187], v[68:71]
	v_mfma_f32_16x16x32_bf16 v[64:67], v[152:155], v[184:187], v[64:67]
	v_mfma_f32_16x16x32_bf16 v[116:119], v[148:151], v[164:167], v[116:119]
	v_mfma_f32_16x16x32_bf16 v[112:115], v[156:159], v[164:167], v[112:115]
	v_mfma_f32_16x16x32_bf16 v[100:103], v[148:151], v[172:175], v[100:103]
	v_mfma_f32_16x16x32_bf16 v[96:99], v[156:159], v[172:175], v[96:99]
	v_mfma_f32_16x16x32_bf16 v[84:87], v[148:151], v[180:183], v[84:87]
	v_mfma_f32_16x16x32_bf16 v[80:83], v[156:159], v[180:183], v[80:83]
	v_mfma_f32_16x16x32_bf16 v[68:71], v[148:151], v[188:191], v[68:71]
	v_mfma_f32_16x16x32_bf16 v[64:67], v[156:159], v[188:191], v[64:67]
	s_setprio 0
	s_barrier
	s_add_i32 m0, s54, 0x17f80
	ds_read_b128 v[160:163], v247 offset:49152
	global_load_lds_dwordx4 v192, s[72:73] offset:128
	s_add_i32 m0, s54, 0x19f80
	ds_read_b128 v[164:167], v247 offset:50176
	global_load_lds_dwordx4 v204, s[72:73] offset:128
	s_add_i32 m0, s54, 0x1bf80
	ds_read_b128 v[168:171], v247 offset:51200
	global_load_lds_dwordx4 v192, s[74:75] offset:128
	s_add_i32 m0, s54, 0x1df80
	ds_read_b128 v[172:175], v247 offset:52224
	global_load_lds_dwordx4 v204, s[74:75] offset:128
	s_add_i32 m0, s59, 0xffffff80
	ds_read_b128 v[176:179], v247 offset:53248
	global_load_lds_dwordx4 v200, s[4:5] offset:128
	s_add_i32 m0, s60, 0xffffff80
	ds_read_b128 v[180:183], v247 offset:54272
	global_load_lds_dwordx4 v202, s[4:5] offset:128
	ds_read_b128 v[184:187], v247 offset:55296
	ds_read_b128 v[188:191], v247 offset:56320
	s_waitcnt vmcnt(8)
	s_waitcnt lgkmcnt(0)
	s_barrier
	s_setprio 1
	s_waitcnt lgkmcnt(0)
	v_mfma_f32_16x16x32_bf16 v[60:63], v[128:131], v[160:163], v[60:63]
	v_mfma_f32_16x16x32_bf16 v[56:59], v[136:139], v[160:163], v[56:59]
	v_mfma_f32_16x16x32_bf16 v[44:47], v[128:131], v[168:171], v[44:47]
	v_mfma_f32_16x16x32_bf16 v[40:43], v[136:139], v[168:171], v[40:43]
	v_mfma_f32_16x16x32_bf16 v[28:31], v[128:131], v[176:179], v[28:31]
	v_mfma_f32_16x16x32_bf16 v[24:27], v[136:139], v[176:179], v[24:27]
	v_mfma_f32_16x16x32_bf16 v[12:15], v[128:131], v[184:187], v[12:15]
	v_mfma_f32_16x16x32_bf16 v[8:11], v[136:139], v[184:187], v[8:11]
	v_mfma_f32_16x16x32_bf16 v[60:63], v[132:135], v[164:167], v[60:63]
	v_mfma_f32_16x16x32_bf16 v[56:59], v[140:143], v[164:167], v[56:59]
	v_mfma_f32_16x16x32_bf16 v[44:47], v[132:135], v[172:175], v[44:47]
	v_mfma_f32_16x16x32_bf16 v[40:43], v[140:143], v[172:175], v[40:43]
	v_mfma_f32_16x16x32_bf16 v[28:31], v[132:135], v[180:183], v[28:31]
	v_mfma_f32_16x16x32_bf16 v[24:27], v[140:143], v[180:183], v[24:27]
	v_mfma_f32_16x16x32_bf16 v[12:15], v[132:135], v[188:191], v[12:15]
	v_mfma_f32_16x16x32_bf16 v[8:11], v[140:143], v[188:191], v[8:11]
	s_setprio 0
	s_setprio 1
	v_mfma_f32_16x16x32_bf16 v[52:55], v[144:147], v[160:163], v[52:55]
	v_mfma_f32_16x16x32_bf16 v[48:51], v[152:155], v[160:163], v[48:51]
	v_mfma_f32_16x16x32_bf16 v[36:39], v[144:147], v[168:171], v[36:39]
	v_mfma_f32_16x16x32_bf16 v[32:35], v[152:155], v[168:171], v[32:35]
	v_mfma_f32_16x16x32_bf16 v[20:23], v[144:147], v[176:179], v[20:23]
	v_mfma_f32_16x16x32_bf16 v[16:19], v[152:155], v[176:179], v[16:19]
	v_mfma_f32_16x16x32_bf16 v[4:7], v[144:147], v[184:187], v[4:7]
	v_mfma_f32_16x16x32_bf16 v[0:3], v[152:155], v[184:187], v[0:3]
	v_mfma_f32_16x16x32_bf16 v[52:55], v[148:151], v[164:167], v[52:55]
	v_mfma_f32_16x16x32_bf16 v[48:51], v[156:159], v[164:167], v[48:51]
	v_mfma_f32_16x16x32_bf16 v[36:39], v[148:151], v[172:175], v[36:39]
	v_mfma_f32_16x16x32_bf16 v[32:35], v[156:159], v[172:175], v[32:35]
	v_mfma_f32_16x16x32_bf16 v[20:23], v[148:151], v[180:183], v[20:23]
	v_mfma_f32_16x16x32_bf16 v[16:19], v[156:159], v[180:183], v[16:19]
	v_mfma_f32_16x16x32_bf16 v[4:7], v[148:151], v[188:191], v[4:7]
	v_mfma_f32_16x16x32_bf16 v[0:3], v[156:159], v[188:191], v[0:3]
	s_setprio 0
	s_barrier
	s_add_u32 s0, s0, 0x100
	s_addc_u32 s1, s1, 0
	s_add_u32 s6, s6, 0x100
	s_addc_u32 s7, s7, 0
	s_cmp_ge_u32 s71, s61
	s_mov_b32 s4, s71
	s_cbranch_scc0 .LBB0_222
